# P8 row-statistics exchange polls the sentinel-initialised slots directly (no vmcnt(0)+counter atomic+counter poll+barrier)
# baseline (speedup 1.0000x reference)
.LBB0_57:
	v_readlane_b32 s0, v254, 5
	v_readlane_b32 s1, v254, 6
	s_cmp_gt_i32 s1, 2
	s_cselect_b64 s[4:5], -1, 0
	s_and_b64 s[0:1], s[6:7], s[4:5]
	s_andn2_b64 vcc, exec, s[0:1]
	s_cbranch_vccnz .LBB0_109
	v_readlane_b32 s0, v254, 2
	s_cmp_gt_u32 s0, 95
	s_cbranch_scc1 .Lsent_done
	s_lshl_b32 s0, s0, 13
	v_lshl_add_u32 v1, v0, 4, s0
	v_mov_b32_e32 v2, -1
	v_mov_b32_e32 v3, -1
	v_mov_b32_e32 v4, -1
	v_mov_b32_e32 v5, -1
	s_add_u32 s0, s26, 0x120000
	s_addc_u32 s1, s27, 0
	global_store_dwordx4 v1, v[2:5], s[0:1]
.Lsent_done:
	s_waitcnt vmcnt(0)
	v_cmp_eq_u32_e32 vcc, 0, v0
	s_waitcnt lgkmcnt(0)
	s_barrier
	s_and_saveexec_b64 s[6:7], vcc
	s_cbranch_execz .LBB0_108
	v_readlane_b32 s0, v254, 8
	s_waitcnt vmcnt(0) expcnt(0) lgkmcnt(0)
	s_nop 0
	v_mov_b32_e32 v1, s0
	ds_read_b32 v3, v1
	ds_read_b32 v1, v1 offset:4
	s_waitcnt lgkmcnt(1)
	v_cmp_ne_u32_e32 vcc, 0, v3
	s_cbranch_vccnz .LBB0_74
	v_readlane_b32 s0, v254, 0
	v_readlane_b32 s1, v254, 1
	s_load_dwordx2 s[10:11], s[0:1], 0x4
	s_add_u32 s0, s26, 0x4200
	s_addc_u32 s1, s27, 0
	s_add_u32 s8, s26, 0x4400
	s_addc_u32 s9, s27, 0
	s_waitcnt lgkmcnt(0)
	s_mul_i32 s35, s10, s33
	s_add_u32 s10, s26, 0x4500
	s_mul_i32 s35, s35, s11
	s_addc_u32 s11, s27, 0
	s_add_u32 s12, s26, 0x4600
	s_addc_u32 s13, s27, 0
	s_add_u32 s14, s26, 0x4700
	s_addc_u32 s15, s27, 0
	s_add_u32 s28, s26, 0x4800
	s_addc_u32 s29, s27, 0
	s_add_u32 s30, s26, 0x4900
	s_addc_u32 s31, s27, 0
	s_add_u32 s38, s26, 0x4a00
	s_addc_u32 s39, s27, 0
	s_add_u32 s40, s26, 0x4b00
	s_addc_u32 s41, s27, 0
	s_add_u32 s42, s26, 0x4c00
	s_addc_u32 s43, s27, 0
	s_add_u32 s44, s26, 0x4d00
	s_addc_u32 s45, s27, 0
	s_add_u32 s46, s26, 0x4e00
	s_addc_u32 s47, s27, 0
	s_add_u32 s48, s26, 0x4f00
	s_addc_u32 s49, s27, 0
	s_add_u32 s54, s26, 0x5000
	s_addc_u32 s55, s27, 0
	s_add_u32 s58, s26, 0x5100
	s_addc_u32 s59, s27, 0
	s_add_u32 s68, s26, 0x5200
	s_addc_u32 s69, s27, 0
	s_add_u32 s74, s26, 0x5300
	s_addc_u32 s75, s27, 0
	s_mov_b32 s70, 1
	v_mov_b32_e32 v17, 0
	s_branch .LBB0_62

.LBB0_1027:
	s_or_b64 exec, exec, s[4:5]
	s_lshl_b32 s3, s3, 8
	s_and_saveexec_b64 s[4:5], s[0:1]
	s_cbranch_execz .LBB0_1042
	s_waitcnt lgkmcnt(0)
	v_add_u32_e32 v150, s3, v148
	v_ashrrev_i32_e32 v151, 31, v150
	v_lshlrev_b64 v[150:151], 5, v[150:151]
	v_lshl_add_u64 v[200:201], s[6:7], 0, v[150:151]
	s_mov_b32 s22, 0x100000
.Lp8x_poll:
	global_load_dword v149, v[200:201], off sc1
	global_load_dword v152, v[200:201], off offset:4 sc1
	global_load_dword v153, v[200:201], off offset:8 sc1
	global_load_dword v154, v[200:201], off offset:12 sc1
	global_load_dword v155, v[200:201], off offset:16 sc1
	global_load_dword v156, v[200:201], off offset:20 sc1
	global_load_dword v157, v[200:201], off offset:24 sc1
	global_load_dword v150, v[200:201], off offset:28 sc1
	s_waitcnt vmcnt(0)
	v_or3_b32 v202, v149, v152, v153
	v_or3_b32 v202, v202, v154, v155
	v_or3_b32 v202, v202, v156, v157
	v_or_b32_e32 v202, v202, v150
	v_cmp_gt_i32_e32 vcc, 0, v202
	s_cbranch_vccz .Lp8x_ready
	s_add_i32 s22, s22, -1
	s_cmp_eq_u32 s22, 0
	s_cbranch_scc1 .Lp8x_ready
	s_sleep 1
	s_branch .Lp8x_poll
.Lp8x_ready:
	v_mov_b32_e32 v151, 0x358637bd
	s_mov_b32 s0, 0xf800000
	v_lshl_add_u32 v148, v148, 2, 0
	s_waitcnt vmcnt(7)
	v_add_f32_e32 v149, 0, v149
	s_waitcnt vmcnt(6)
	v_add_f32_e32 v149, v149, v152
	s_waitcnt vmcnt(5)
	v_add_f32_e32 v149, v149, v153
	s_waitcnt vmcnt(4)
	v_add_f32_e32 v149, v149, v154
	s_waitcnt vmcnt(3)
	v_add_f32_e32 v149, v149, v155
	s_waitcnt vmcnt(2)
	v_add_f32_e32 v149, v149, v156
	s_waitcnt vmcnt(1)
	v_add_f32_e32 v149, v149, v157
	s_waitcnt vmcnt(0)
	v_add_f32_e32 v149, v149, v150
	v_fmac_f32_e32 v151, 0x3a000000, v149
	v_mul_f32_e32 v149, 0x4f800000, v151
	v_cmp_gt_f32_e32 vcc, s0, v151
	s_nop 1
	v_cndmask_b32_e32 v149, v151, v149, vcc
	v_sqrt_f32_e32 v150, v149
	v_mov_b32_e32 v151, 0x260
	v_add_u32_e32 v152, -1, v150
	v_add_u32_e32 v153, 1, v150
	v_fma_f32 v154, -v152, v150, v149
	v_fma_f32 v155, -v153, v150, v149
	v_cmp_ge_f32_e64 s[0:1], 0, v154
	s_nop 1
	v_cndmask_b32_e64 v150, v150, v152, s[0:1]
	v_cmp_lt_f32_e64 s[0:1], 0, v155
	s_nop 1
	v_cndmask_b32_e64 v150, v150, v153, s[0:1]
	v_mul_f32_e32 v152, 0x37800000, v150
	v_cndmask_b32_e32 v150, v150, v152, vcc
	v_cmp_class_f32_e32 vcc, v149, v151
	s_nop 1
	v_cndmask_b32_e32 v149, v150, v149, vcc
	v_div_scale_f32 v150, s[0:1], v149, v149, 1.0
	v_rcp_f32_e32 v151, v150
	v_div_scale_f32 v152, vcc, 1.0, v149, 1.0
	v_fma_f32 v153, -v150, v151, 1.0
	v_fmac_f32_e32 v151, v153, v151
	v_mul_f32_e32 v153, v152, v151
	v_fma_f32 v154, -v150, v153, v152
	v_fmac_f32_e32 v153, v154, v151
	v_fma_f32 v150, -v150, v153, v152
	v_div_fmas_f32 v150, v150, v151, v153
	v_div_fixup_f32 v149, v150, v149, 1.0
	ds_write_b32 v148, v149 offset:8192
